# coalesced-wait variant re-padded so that all code after the scan phase keeps the baseline's placement modulo 256 bytes
# speedup vs baseline: 1.0151x; 1.0019x over previous
.Lmy_ck_drE_h:
	s_waitcnt lgkmcnt(0)
	s_bfe_u32 s96, s62, 0x20006
	s_and_b32 s97, s96, 1
	s_mul_i32 s97, s97, 0x2700
	s_mov_b32 s101, 0x1c000
	s_mov_b32 s100, 0x6100
	s_bitcmp0_b32 s65, 0
	s_cselect_b32 s101, 0xe000, s101
	s_cselect_b32 s100, 0x4e00, s100
	s_cmp_gt_u32 s96, 1
	s_cselect_b32 s100, s100, 0
	s_add_i32 s97, s97, s101
	s_add_i32 s97, s97, s100
	s_mov_b32 s96, s97
	v_and_b32_e32 v72, 3, v233
	v_lshrrev_b32_e32 v73, 2, v233
	v_lshlrev_b32_e32 v72, 2, v72
	v_lshl_add_u32 v72, v73, 8, v72
	v_lshl_add_u32 v72, v234, 6, v72
	s_add_i32 s97, s96, 0x1000
	v_add_u32_e32 v78, s97, v72
	v_xor_b32_e32 v79, v224, v234
	v_lshl_add_u32 v79, v79, 4, s96
	ds_read_b128 v[96:99], v79
	ds_read_b128 v[100:103], v79 offset:1024
	ds_read_b128 v[104:107], v79 offset:2048
	ds_read_b128 v[108:111], v79 offset:3072
	ds_read_b32 v80, v78
	ds_read_b32 v81, v78 offset:16
	ds_read_b32 v82, v78 offset:32
	ds_read_b32 v83, v78 offset:48
	ds_read_b32 v84, v78 offset:1024
	ds_read_b32 v85, v78 offset:1040
	ds_read_b32 v86, v78 offset:1056
	ds_read_b32 v87, v78 offset:1072
	ds_read_b32 v88, v78 offset:2048
	ds_read_b32 v89, v78 offset:2064
	ds_read_b32 v90, v78 offset:2080
	ds_read_b32 v91, v78 offset:2096
	ds_read_b32 v92, v78 offset:3072
	ds_read_b32 v93, v78 offset:3088
	ds_read_b32 v94, v78 offset:3104
	ds_read_b32 v95, v78 offset:3120
	v_lshl_add_u32 v74, v224, 2, s96
	ds_write_b32 v74, v235 offset:9728
	v_add_u32_e32 v75, -1, v233
	v_mov_b32_e32 v76, -1
	v_cndmask_b32_e64 v75, v76, v75, s[98:99]
	v_cmp_lt_u32_e64 s[100:101], 7, v233
	v_add_u32_e32 v76, -8, v233
	v_and_b32_e32 v77, 1, v234
	v_cndmask_b32_e64 v75, v75, v76, s[100:101]
	v_lshlrev_b32_e32 v77, 2, v77
	v_sub_u32_e32 v76, v75, v77
	v_lshlrev_b32_e32 v77, 2, v234
	v_sub_u32_e32 v77, v233, v77
	v_add_u32_e32 v77, -1, v77
	s_waitcnt lgkmcnt(10)
	v_mfma_f32_16x16x4_f32 v[244:247], v80, v96, 0
	v_mfma_f32_16x16x4_f32 v[240:243], v81, v97, 0
	v_mfma_f32_16x16x4_f32 v[244:247], v82, v98, v[244:247]
	v_mfma_f32_16x16x4_f32 v[240:243], v83, v99, v[240:243]
	v_mfma_f32_16x16x4_f32 v[244:247], v84, v100, v[244:247]
	v_mfma_f32_16x16x4_f32 v[240:243], v85, v101, v[240:243]
	v_mfma_f32_16x16x4_f32 v[244:247], v86, v102, v[244:247]
	s_waitcnt lgkmcnt(2)
	v_mfma_f32_16x16x4_f32 v[240:243], v87, v103, v[240:243]
	v_mfma_f32_16x16x4_f32 v[244:247], v88, v104, v[244:247]
	v_mfma_f32_16x16x4_f32 v[240:243], v89, v105, v[240:243]
	v_mfma_f32_16x16x4_f32 v[244:247], v90, v106, v[244:247]
	v_mfma_f32_16x16x4_f32 v[240:243], v91, v107, v[240:243]
	v_mfma_f32_16x16x4_f32 v[244:247], v92, v108, v[244:247]
	v_mfma_f32_16x16x4_f32 v[240:243], v93, v109, v[240:243]
	v_mfma_f32_16x16x4_f32 v[244:247], v94, v110, v[244:247]
	s_waitcnt lgkmcnt(1)
	v_mfma_f32_16x16x4_f32 v[240:243], v95, v111, v[240:243]
	s_nop 9
	v_add_f32_e32 v244, v244, v240
	v_add_f32_e32 v245, v245, v241
	v_add_f32_e32 v246, v246, v242
	v_add_f32_e32 v247, v247, v243
	v_cmp_le_i32_e64 s[96:97], 0, v76
	v_cmp_le_i32_e64 s[100:101], 1, v76
	s_nop 0
	v_cndmask_b32_e64 v128, 0, v244, s[96:97]
	v_cndmask_b32_e64 v129, 0, v245, s[100:101]
	v_cmp_le_i32_e64 s[96:97], 2, v76
	v_cmp_le_i32_e64 s[100:101], 3, v76
	s_nop 0
	v_cndmask_b32_e64 v130, 0, v246, s[96:97]
	v_cndmask_b32_e64 v131, 0, v247, s[100:101]
	s_bfe_u32 s96, s62, 0x20006
	s_and_b32 s97, s96, 1
	s_mul_i32 s97, s97, 0x2700
	s_mov_b32 s101, 0x1c000
	s_mov_b32 s100, 0x6100
	s_bitcmp0_b32 s65, 0
	s_cselect_b32 s101, 0xe000, s101
	s_cselect_b32 s100, 0x4e00, s100
	s_cmp_gt_u32 s96, 1
	s_cselect_b32 s100, s100, 0
	s_add_i32 s97, s97, s101
	s_add_i32 s97, s97, s100
	v_xor_b32_e32 v74, v224, v234
	v_lshl_add_u32 v74, v74, 4, s97
	ds_write_b128 v74, v[128:131] offset:8448
	v_lshlrev_b32_e32 v75, 7, v234
	v_lshl_add_u32 v75, v233, 2, v75
	v_add_u32_e32 v75, s97, v75
	v_cmp_le_i32_e64 s[96:97], 0, v77
	v_cmp_le_i32_e64 s[100:101], 1, v77
	s_nop 0
	v_cndmask_b32_e64 v132, 0, v244, s[96:97]
	v_cndmask_b32_e64 v133, 0, v245, s[100:101]
	v_cmp_le_i32_e64 s[96:97], 2, v77
	v_cmp_le_i32_e64 s[100:101], 3, v77
	s_nop 0
	v_cndmask_b32_e64 v134, 0, v246, s[96:97]
	v_cndmask_b32_e64 v135, 0, v247, s[100:101]
	s_mov_b64 exec, 0x00ff00ff
	ds_write_b32 v75, v132 offset:9472
	ds_write_b32 v75, v133 offset:9504
	ds_write_b32 v75, v134 offset:9536
	ds_write_b32 v75, v135 offset:9568
	s_mov_b64 exec, -1
	s_branch .LBB0_655
	s_nop 0
	s_nop 0
	s_nop 0
	s_nop 0
	s_nop 0
	s_nop 0
	s_nop 0
	s_nop 0
	s_nop 0
	s_nop 0
	s_nop 0
	s_nop 0
	s_nop 0
	s_nop 0
